# GLA sample-item loops: nt hint on the streamed dword/dwordx4 state loads and stores
# baseline (speedup 1.0000x reference)
.LBB0_308:
	v_add_u32_e32 v1, s16, v168
	s_load_dwordx16 s[68:83], s[0:1], 0x40
	v_and_b32_e32 v2, 3, v1
	v_lshlrev_b32_e32 v0, 7, v2
	v_or_b32_e32 v3, v0, v180
	v_or_b32_e32 v4, v0, v181
	v_or_b32_e32 v5, v0, v182
	v_or_b32_e32 v6, v0, v183
	v_or_b32_e32 v7, v0, v185
	s_waitcnt vmcnt(22)
	v_or_b32_e32 v8, v0, v186
	v_or_b32_e32 v9, v0, v187
	v_or_b32_e32 v10, v0, v188
	v_lshlrev_b32_e32 v3, 2, v3
	v_lshlrev_b32_e32 v4, 2, v4
	v_lshlrev_b32_e32 v5, 2, v5
	v_lshlrev_b32_e32 v6, 2, v6
	v_lshlrev_b32_e32 v7, 2, v7
	v_lshlrev_b32_e32 v8, 2, v8
	v_lshlrev_b32_e32 v9, 2, v9
	v_lshlrev_b32_e32 v10, 2, v10
	s_waitcnt lgkmcnt(0)
	s_barrier
	global_load_dword v3, v3, s[76:77] nt
	s_nop 0
	global_load_dword v4, v4, s[76:77] nt
	s_nop 0
	global_load_dword v5, v5, s[76:77] nt
	s_nop 0
	global_load_dword v6, v6, s[76:77] nt
	s_nop 0
	global_load_dword v7, v7, s[76:77] nt
	s_nop 0
	global_load_dword v8, v8, s[76:77] nt
	s_nop 0
	global_load_dword v9, v9, s[76:77] nt
	s_nop 0
	global_load_dword v10, v10, s[76:77] nt
	s_waitcnt vmcnt(6)
	ds_write2st64_b32 v178, v3, v4 offset1:4
	s_waitcnt vmcnt(4)
	ds_write_b32 v184, v6
	s_waitcnt vmcnt(3)
	ds_write2st64_b32 v178, v5, v7 offset0:8 offset1:16
	s_waitcnt vmcnt(1)
	ds_write2st64_b32 v178, v8, v9 offset0:20 offset1:24
	s_waitcnt vmcnt(0)
	ds_write_b32 v189, v10
	s_and_saveexec_b64 s[14:15], s[4:5]
	s_cbranch_execz .LBB0_310
	s_load_dwordx16 s[68:83], s[0:1], 0x40
	v_or_b32_e32 v3, v0, v80
	v_lshlrev_b32_e32 v3, 2, v3
	s_waitcnt lgkmcnt(0)
	global_load_dword v3, v3, s[78:79] nt
	s_waitcnt vmcnt(0)
	ds_write_b32 v178, v3 offset:8192

.LBB0_317:
	v_lshl_add_u64 v[0:1], v[102:103], 0, v[70:71]
	global_load_dword v98, v[0:1], off nt
	global_load_dword v106, v[0:1], off offset:1024 nt
	global_load_dword v66, v[0:1], off offset:2048 nt
	global_load_dword v64, v[0:1], off offset:3072 nt
	v_add_co_u32_e32 v2, vcc, 0x1000, v0
	v_mov_b32_e32 v107, v99
	s_nop 0
	v_addc_co_u32_e32 v3, vcc, 0, v1, vcc
	global_load_dword v62, v[2:3], off nt
	global_load_dword v130, v[2:3], off offset:1024 nt
	global_load_dword v132, v[2:3], off offset:2048 nt
	global_load_dword v138, v[2:3], off offset:3072 nt
	v_add_co_u32_e32 v2, vcc, 0x2000, v0
	v_mov_b32_e32 v67, v99
	s_nop 0
	v_addc_co_u32_e32 v3, vcc, 0, v1, vcc
	global_load_dword v140, v[2:3], off nt
	global_load_dword v136, v[2:3], off offset:1024 nt
	global_load_dword v134, v[2:3], off offset:2048 nt
	global_load_dword v124, v[2:3], off offset:3072 nt
	v_add_co_u32_e32 v0, vcc, 0x3000, v0
	v_mov_b32_e32 v65, v99
	s_nop 0
	v_addc_co_u32_e32 v1, vcc, 0, v1, vcc
	global_load_dword v122, v[0:1], off nt
	global_load_dword v120, v[0:1], off offset:1024 nt
	global_load_dword v116, v[0:1], off offset:2048 nt
	global_load_dword v114, v[0:1], off offset:3072 nt
	ds_read_b128 v[0:3], v87 offset:4096
	ds_read_b128 v[52:55], v87 offset:2048
	ds_read_b128 v[56:59], v87 offset:4608
	ds_read_b128 v[12:15], v87 offset:2560
	ds_read_b128 v[8:11], v87 offset:5120
	ds_read_b128 v[48:51], v87 offset:3072
	ds_read_b128 v[44:47], v87 offset:5632
	ds_read_b128 v[40:43], v87 offset:3584
	ds_read_b128 v[36:39], v87 offset:4112
	ds_read_b128 v[24:27], v87 offset:2064
	s_waitcnt lgkmcnt(5)
	v_mov_b32_e32 v148, v8
	v_mov_b32_e32 v104, v0
	v_mov_b32_e32 v108, v1
	v_mov_b32_e32 v126, v2
	v_mov_b32_e32 v112, v3
	ds_read_b128 v[142:145], v87
	ds_read_b128 v[16:19], v87 offset:16
	ds_read_b128 v[4:7], v87 offset:32
	ds_read_b128 v[0:3], v87 offset:48
	ds_read_b128 v[28:31], v87 offset:4624
	ds_read_b128 v[32:35], v87 offset:2576
	ds_read_b128 v[20:23], v87 offset:528
	ds_read_b128 v[150:153], v87 offset:512
	v_mov_b32_e32 v105, v52
	s_waitcnt lgkmcnt(9)
	v_mov_b32_e32 v154, v36
	v_mul_f32_e32 v36, v52, v99
	v_mov_b32_e32 v109, v53
	v_mul_f32_e32 v8, v53, v99
	v_mov_b32_e32 v127, v54
	s_waitcnt lgkmcnt(7)
	v_mov_b32_e32 v146, v142
	s_waitcnt lgkmcnt(0)
	v_mov_b32_e32 v147, v150
	v_mov_b32_e32 v150, v143
	v_mov_b32_e32 v113, v55
	v_mov_b32_e32 v142, v10
	v_mul_f32_e32 v10, v55, v99
	v_mov_b32_e32 v155, v24
	v_mov_b32_e32 v63, v99
	v_mov_b32_e32 v149, v48
	v_mov_b32_e32 v143, v50
	v_mov_b32_e32 v131, v99
	v_mov_b32_e32 v133, v99
	v_mov_b32_e32 v139, v99
	v_mov_b32_e32 v141, v99
	v_mov_b32_e32 v137, v99
	v_mov_b32_e32 v135, v99
	v_mov_b32_e32 v125, v99
	v_mov_b32_e32 v123, v99
	v_mov_b32_e32 v121, v99
	v_mov_b32_e32 v117, v99
	v_mov_b32_e32 v115, v99
	s_add_i32 s14, s14, 16
	v_lshl_add_u64 v[102:103], v[102:103], 0, s[12:13]
	s_cmpk_lt_u32 s14, 0x70
	s_waitcnt vmcnt(15)
	v_pk_fma_f32 v[110:111], v[104:105], v[98:99], v[36:37] op_sel_hi:[1,1,0]
	v_mov_b32_e32 v104, v56
	v_mov_b32_e32 v105, v12
	v_mov_b32_e32 v111, v77
	v_mul_f32_e32 v12, v12, v77
	s_waitcnt vmcnt(14)
	v_pk_fma_f32 v[52:53], v[108:109], v[106:107], v[8:9] op_sel_hi:[1,1,0]
	v_pk_fma_f32 v[104:105], v[104:105], v[110:111], v[12:13] op_sel_hi:[1,1,0]
	v_mov_b32_e32 v12, v57
	v_mov_b32_e32 v53, v77
	v_mul_f32_e32 v8, v13, v77
	v_mov_b32_e32 v111, v104
	v_pk_fma_f32 v[106:107], v[12:13], v[52:53], v[8:9] op_sel_hi:[1,1,0]
	v_mul_f32_e32 v8, v54, v99
	v_pk_fma_f32 v[60:61], v[146:147], v[110:111], v[60:61]
	v_mov_b32_e32 v53, v106
	v_mov_b32_e32 v110, v9
	s_waitcnt vmcnt(13)
	v_pk_fma_f32 v[8:9], v[126:127], v[66:67], v[8:9] op_sel_hi:[1,1,0]
	v_pk_fma_f32 v[12:13], v[150:151], v[52:53], v[60:61]
	v_mov_b32_e32 v52, v58
	v_mov_b32_e32 v53, v14
	v_mov_b32_e32 v9, v77
	v_mul_f32_e32 v14, v14, v77
	v_pk_fma_f32 v[108:109], v[52:53], v[8:9], v[14:15] op_sel_hi:[1,1,0]
	v_mov_b32_e32 v52, v144
	v_mov_b32_e32 v53, v152
	v_mov_b32_e32 v9, v108
	v_pk_fma_f32 v[8:9], v[52:53], v[8:9], v[12:13]
	s_waitcnt vmcnt(12)
	v_pk_fma_f32 v[12:13], v[112:113], v[64:65], v[10:11] op_sel_hi:[1,1,0]
	v_mov_b32_e32 v14, v59
	v_mov_b32_e32 v13, v77
	v_mul_f32_e32 v10, v15, v77
	v_pk_fma_f32 v[112:113], v[14:15], v[12:13], v[10:11] op_sel_hi:[1,1,0]
	v_mul_f32_e32 v10, v24, v99
	v_mov_b32_e32 v152, v145
	v_mov_b32_e32 v13, v112
	v_mov_b32_e32 v146, v11
	s_waitcnt vmcnt(11)
	v_pk_fma_f32 v[10:11], v[154:155], v[62:63], v[10:11] op_sel_hi:[1,1,0]
	v_pk_fma_f32 v[8:9], v[152:153], v[12:13], v[8:9]
	v_mov_b32_e32 v12, v28
	v_mov_b32_e32 v13, v32
	v_mov_b32_e32 v11, v77
	v_mul_f32_e32 v14, v32, v77
	v_pk_fma_f32 v[144:145], v[12:13], v[10:11], v[14:15] op_sel_hi:[1,1,0]
	v_mov_b32_e32 v105, v81
	v_mov_b32_e32 v12, v16
	v_mov_b32_e32 v13, v20
	v_mov_b32_e32 v11, v144
	v_mul_f32_e32 v16, v48, v81
	v_pk_fma_f32 v[126:127], v[12:13], v[10:11], v[8:9]
	ds_read_b128 v[52:55], v87 offset:5136
	ds_read_b128 v[56:59], v87 offset:3088
	ds_read_b128 v[8:11], v87 offset:1040
	ds_read_b128 v[60:63], v87 offset:5648
	ds_read_b128 v[64:67], v87 offset:3600
	ds_read_b128 v[12:15], v87 offset:1552
	v_pk_fma_f32 v[158:159], v[148:149], v[104:105], v[16:17] op_sel_hi:[1,1,0]
	ds_read_b128 v[148:151], v87 offset:1024
	ds_read_b128 v[152:155], v87 offset:1536
	v_mov_b32_e32 v104, v44
	v_mov_b32_e32 v105, v40
	v_mov_b32_e32 v159, v85
	v_mul_f32_e32 v16, v40, v85
	v_mov_b32_e32 v111, v49
	v_mov_b32_e32 v107, v81
	v_pk_fma_f32 v[104:105], v[104:105], v[158:159], v[16:17] op_sel_hi:[1,1,0]
	v_mul_f32_e32 v16, v49, v81
	v_pk_fma_f32 v[48:49], v[110:111], v[106:107], v[16:17] op_sel_hi:[1,1,0]
	v_mov_b32_e32 v40, v45
	v_mov_b32_e32 v49, v85
	v_mul_f32_e32 v16, v41, v85
	v_mov_b32_e32 v109, v81
	s_waitcnt lgkmcnt(1)
	v_mov_b32_e32 v160, v148
	s_waitcnt lgkmcnt(0)
	v_mov_b32_e32 v161, v152
	v_mov_b32_e32 v159, v104
	v_pk_fma_f32 v[106:107], v[40:41], v[48:49], v[16:17] op_sel_hi:[1,1,0]
	v_mul_f32_e32 v16, v50, v81
	v_pk_fma_f32 v[118:119], v[160:161], v[158:159], v[118:119]
	v_mov_b32_e32 v152, v149
	v_mov_b32_e32 v49, v106
	v_pk_fma_f32 v[44:45], v[142:143], v[108:109], v[16:17] op_sel_hi:[1,1,0]
	v_pk_fma_f32 v[40:41], v[152:153], v[48:49], v[118:119]
	v_mov_b32_e32 v48, v46
	v_mov_b32_e32 v49, v42
	v_mov_b32_e32 v45, v85
	v_mul_f32_e32 v16, v42, v85
	v_pk_fma_f32 v[108:109], v[48:49], v[44:45], v[16:17] op_sel_hi:[1,1,0]
	v_mov_b32_e32 v147, v51
	v_mov_b32_e32 v113, v81
	v_mov_b32_e32 v48, v150
	v_mov_b32_e32 v49, v154
	v_mov_b32_e32 v45, v108
	v_mul_f32_e32 v16, v51, v81
	v_pk_fma_f32 v[40:41], v[48:49], v[44:45], v[40:41]
	v_pk_fma_f32 v[44:45], v[146:147], v[112:113], v[16:17] op_sel_hi:[1,1,0]
	v_mov_b32_e32 v42, v47
	v_mov_b32_e32 v45, v85
	v_mul_f32_e32 v16, v43, v85
	v_mov_b32_e32 v156, v52
	v_mov_b32_e32 v157, v56
	v_mov_b32_e32 v145, v81
	v_pk_fma_f32 v[110:111], v[42:43], v[44:45], v[16:17] op_sel_hi:[1,1,0]
	v_mul_f32_e32 v16, v56, v81
	v_mov_b32_e32 v154, v151
	v_mov_b32_e32 v45, v110
	v_pk_fma_f32 v[42:43], v[156:157], v[144:145], v[16:17] op_sel_hi:[1,1,0]
	v_pk_fma_f32 v[40:41], v[154:155], v[44:45], v[40:41]
	v_mov_b32_e32 v44, v60
	v_mov_b32_e32 v45, v64
	v_mov_b32_e32 v43, v85
	v_mul_f32_e32 v16, v64, v85
	v_pk_fma_f32 v[112:113], v[44:45], v[42:43], v[16:17] op_sel_hi:[1,1,0]
	v_mov_b32_e32 v44, v8
	v_mov_b32_e32 v24, v37
	v_mul_f32_e32 v8, v25, v99
	s_waitcnt vmcnt(10)
	v_pk_fma_f32 v[142:143], v[24:25], v[130:131], v[8:9] op_sel_hi:[1,1,0]
	v_mov_b32_e32 v32, v29
	v_mov_b32_e32 v143, v77
	v_mul_f32_e32 v8, v33, v77
	v_pk_fma_f32 v[24:25], v[32:33], v[142:143], v[8:9] op_sel_hi:[1,1,0]
	v_mov_b32_e32 v56, v53
	v_mov_b32_e32 v25, v81
	v_mul_f32_e32 v8, v57, v81
	v_pk_fma_f32 v[130:131], v[56:57], v[24:25], v[8:9] op_sel_hi:[1,1,0]
	v_mov_b32_e32 v64, v61
	v_mov_b32_e32 v131, v85
	v_mul_f32_e32 v8, v65, v85
	v_mov_b32_e32 v45, v12
	v_mov_b32_e32 v20, v17
	v_mov_b32_e32 v143, v24
	v_pk_fma_f32 v[16:17], v[64:65], v[130:131], v[8:9] op_sel_hi:[1,1,0]
	v_mov_b32_e32 v12, v9
	v_mov_b32_e32 v8, v38
	v_mov_b32_e32 v9, v26
	v_mul_f32_e32 v24, v26, v99
	s_waitcnt vmcnt(9)
	v_pk_fma_f32 v[144:145], v[8:9], v[132:133], v[24:25] op_sel_hi:[1,1,0]
	v_mov_b32_e32 v8, v30
	v_mov_b32_e32 v9, v34
	v_mov_b32_e32 v145, v77
	v_mul_f32_e32 v24, v34, v77
	v_pk_fma_f32 v[146:147], v[8:9], v[144:145], v[24:25] op_sel_hi:[1,1,0]
	v_mov_b32_e32 v8, v54
	v_mov_b32_e32 v9, v58
	v_mov_b32_e32 v147, v81
	v_mul_f32_e32 v24, v58, v81
	v_pk_fma_f32 v[132:133], v[8:9], v[146:147], v[24:25] op_sel_hi:[1,1,0]
	v_mov_b32_e32 v8, v62
	v_mov_b32_e32 v9, v66
	v_mov_b32_e32 v133, v85
	v_mul_f32_e32 v24, v66, v85
	v_pk_fma_f32 v[8:9], v[8:9], v[132:133], v[24:25] op_sel_hi:[1,1,0]
	v_mov_b32_e32 v26, v39
	v_mul_f32_e32 v24, v27, v99
	s_waitcnt vmcnt(8)
	v_pk_fma_f32 v[152:153], v[26:27], v[138:139], v[24:25] op_sel_hi:[1,1,0]
	v_mov_b32_e32 v34, v31
	v_mov_b32_e32 v153, v77
	v_mul_f32_e32 v24, v35, v77
	v_pk_fma_f32 v[156:157], v[34:35], v[152:153], v[24:25] op_sel_hi:[1,1,0]
	v_mov_b32_e32 v58, v55
	v_mov_b32_e32 v157, v81
	v_mul_f32_e32 v24, v59, v81
	v_pk_fma_f32 v[138:139], v[58:59], v[156:157], v[24:25] op_sel_hi:[1,1,0]
	v_mov_b32_e32 v66, v63
	v_mov_b32_e32 v139, v85
	v_mul_f32_e32 v24, v67, v85
	v_pk_fma_f32 v[54:55], v[66:67], v[138:139], v[24:25] op_sel_hi:[1,1,0]
	ds_read_b128 v[62:65], v87 offset:4128
	ds_read_b128 v[24:27], v87 offset:2080
	v_mov_b32_e32 v43, v112
	v_pk_fma_f32 v[118:119], v[44:45], v[42:43], v[40:41]
	v_pk_fma_f32 v[20:21], v[20:21], v[142:143], v[126:127]
	s_waitcnt lgkmcnt(1)
	v_mov_b32_e32 v28, v62
	s_waitcnt lgkmcnt(0)
	v_mov_b32_e32 v29, v24
	v_mul_f32_e32 v24, v24, v99
	s_waitcnt vmcnt(7)
	v_pk_fma_f32 v[60:61], v[28:29], v[140:141], v[24:25] op_sel_hi:[1,1,0]
	ds_read_b128 v[32:35], v87 offset:4640
	ds_read_b128 v[28:31], v87 offset:2592
	v_mov_b32_e32 v61, v77
	v_mov_b32_e32 v145, v146
	v_mov_b32_e32 v153, v156
	s_waitcnt lgkmcnt(1)
	v_mov_b32_e32 v36, v32
	s_waitcnt lgkmcnt(0)
	v_mov_b32_e32 v37, v28
	v_mul_f32_e32 v24, v28, v77
	v_pk_fma_f32 v[140:141], v[36:37], v[60:61], v[24:25] op_sel_hi:[1,1,0]
	ds_read_b128 v[40:43], v87 offset:5152
	ds_read_b128 v[36:39], v87 offset:3104
	v_mov_b32_e32 v141, v81
	v_mul_f32_e32 v28, v25, v99
	v_mov_b32_e32 v61, v140
	s_waitcnt lgkmcnt(1)
	v_mov_b32_e32 v44, v40
	s_waitcnt lgkmcnt(0)
	v_mov_b32_e32 v45, v36
	v_mul_f32_e32 v24, v36, v81
	v_pk_fma_f32 v[66:67], v[44:45], v[140:141], v[24:25] op_sel_hi:[1,1,0]
	ds_read_b128 v[48:51], v87 offset:5664
	ds_read_b128 v[44:47], v87 offset:3616
	v_mov_b32_e32 v67, v85
	v_mov_b32_e32 v36, v41
	v_mov_b32_e32 v131, v16
	s_waitcnt lgkmcnt(1)
	v_mov_b32_e32 v52, v48
	s_waitcnt lgkmcnt(0)
	v_mov_b32_e32 v53, v44
	v_mul_f32_e32 v24, v44, v85
	v_pk_fma_f32 v[52:53], v[52:53], v[66:67], v[24:25] op_sel_hi:[1,1,0]
	v_mov_b32_e32 v24, v63
	s_waitcnt vmcnt(6)
	v_pk_fma_f32 v[148:149], v[24:25], v[136:137], v[28:29] op_sel_hi:[1,1,0]
	v_mov_b32_e32 v28, v33
	v_mov_b32_e32 v149, v77
	v_mul_f32_e32 v24, v29, v77
	v_pk_fma_f32 v[150:151], v[28:29], v[148:149], v[24:25] op_sel_hi:[1,1,0]
	v_mul_f32_e32 v24, v37, v81
	v_mov_b32_e32 v151, v81
	v_pk_fma_f32 v[136:137], v[36:37], v[150:151], v[24:25] op_sel_hi:[1,1,0]
	v_mov_b32_e32 v44, v49
	v_mov_b32_e32 v137, v85
	v_mul_f32_e32 v24, v45, v85
	v_pk_fma_f32 v[56:57], v[44:45], v[136:137], v[24:25] op_sel_hi:[1,1,0]
	v_mov_b32_e32 v24, v64
	v_mov_b32_e32 v25, v26
	v_mul_f32_e32 v26, v26, v99
	s_waitcnt vmcnt(5)
	v_pk_fma_f32 v[154:155], v[24:25], v[134:135], v[26:27] op_sel_hi:[1,1,0]
	v_mov_b32_e32 v24, v34
	v_mov_b32_e32 v25, v30
	v_mov_b32_e32 v155, v77
	v_mul_f32_e32 v26, v30, v77
	v_pk_fma_f32 v[158:159], v[24:25], v[154:155], v[26:27] op_sel_hi:[1,1,0]
	v_mov_b32_e32 v24, v42
	v_mov_b32_e32 v25, v38
	v_mov_b32_e32 v159, v81
	v_mul_f32_e32 v26, v38, v81
	v_pk_fma_f32 v[134:135], v[24:25], v[158:159], v[26:27] op_sel_hi:[1,1,0]
	v_mov_b32_e32 v24, v50
	v_mov_b32_e32 v25, v46
	v_mov_b32_e32 v135, v85
	v_mul_f32_e32 v26, v46, v85
	v_pk_fma_f32 v[58:59], v[24:25], v[134:135], v[26:27] op_sel_hi:[1,1,0]
	v_mov_b32_e32 v26, v65
	v_mul_f32_e32 v24, v27, v99
	s_waitcnt vmcnt(4)
	v_pk_fma_f32 v[160:161], v[26:27], v[124:125], v[24:25] op_sel_hi:[1,1,0]
	v_mov_b32_e32 v30, v35
	v_mov_b32_e32 v161, v77
	v_mul_f32_e32 v24, v31, v77
	v_pk_fma_f32 v[162:163], v[30:31], v[160:161], v[24:25] op_sel_hi:[1,1,0]
	v_mov_b32_e32 v46, v51
	ds_read_b128 v[198:201], v87 offset:4144
	ds_read_b128 v[48:51], v87 offset:2096
	v_mov_b32_e32 v38, v43
	v_mov_b32_e32 v163, v81
	v_mul_f32_e32 v24, v39, v81
	v_pk_fma_f32 v[124:125], v[38:39], v[162:163], v[24:25] op_sel_hi:[1,1,0]
	ds_read_b128 v[36:39], v87 offset:4656
	ds_read_b128 v[40:43], v87 offset:2608
	v_mov_b32_e32 v125, v85
	v_mul_f32_e32 v24, v47, v85
	v_pk_fma_f32 v[62:63], v[46:47], v[124:125], v[24:25] op_sel_hi:[1,1,0]
	ds_read_b128 v[44:47], v87 offset:5168
	ds_read_b128 v[32:35], v87 offset:3120
	s_waitcnt lgkmcnt(5)
	v_mov_b32_e32 v24, v198
	s_waitcnt lgkmcnt(4)
	v_mov_b32_e32 v25, v48
	v_mul_f32_e32 v26, v48, v99
	s_waitcnt vmcnt(3)
	v_pk_fma_f32 v[164:165], v[24:25], v[122:123], v[26:27] op_sel_hi:[1,1,0]
	s_waitcnt lgkmcnt(3)
	v_mov_b32_e32 v24, v36
	s_waitcnt lgkmcnt(2)
	v_mov_b32_e32 v25, v40
	v_mov_b32_e32 v165, v77
	v_mul_f32_e32 v26, v40, v77
	v_pk_fma_f32 v[166:167], v[24:25], v[164:165], v[26:27] op_sel_hi:[1,1,0]
	s_waitcnt lgkmcnt(1)
	v_mov_b32_e32 v24, v44
	s_waitcnt lgkmcnt(0)
	v_mov_b32_e32 v25, v32
	v_mov_b32_e32 v167, v81
	v_mul_f32_e32 v26, v32, v81
	v_pk_fma_f32 v[122:123], v[24:25], v[166:167], v[26:27] op_sel_hi:[1,1,0]
	ds_read_b128 v[28:31], v87 offset:5680
	ds_read_b128 v[24:27], v87 offset:3632
	v_mov_b32_e32 v123, v85
	v_mov_b32_e32 v48, v199
	v_mov_b32_e32 v149, v150
	s_waitcnt lgkmcnt(1)
	v_mov_b32_e32 v64, v28
	s_waitcnt lgkmcnt(0)
	v_mov_b32_e32 v65, v24
	v_mul_f32_e32 v24, v24, v85
	v_pk_fma_f32 v[64:65], v[64:65], v[122:123], v[24:25] op_sel_hi:[1,1,0]
	v_mul_f32_e32 v24, v49, v99
	s_waitcnt vmcnt(2)
	v_pk_fma_f32 v[48:49], v[48:49], v[120:121], v[24:25] op_sel_hi:[1,1,0]
	v_mov_b32_e32 v120, v18
	v_mov_b32_e32 v121, v22
	v_pk_fma_f32 v[20:21], v[120:121], v[144:145], v[20:21]
	v_mov_b32_e32 v22, v19
	v_pk_fma_f32 v[22:23], v[22:23], v[152:153], v[20:21]
	ds_read_b128 v[18:21], v87 offset:544
	v_mov_b32_e32 v120, v4
	v_mov_b32_e32 v40, v37
	v_mov_b32_e32 v49, v77
	v_mul_f32_e32 v24, v41, v77
	s_waitcnt lgkmcnt(0)
	v_mov_b32_e32 v121, v18
	v_pk_fma_f32 v[22:23], v[120:121], v[60:61], v[22:23]
	v_mov_b32_e32 v18, v5
	v_pk_fma_f32 v[4:5], v[18:19], v[148:149], v[22:23]
	v_mov_b32_e32 v18, v6
	v_mov_b32_e32 v19, v20
	v_mov_b32_e32 v155, v158
	v_pk_fma_f32 v[40:41], v[40:41], v[48:49], v[24:25] op_sel_hi:[1,1,0]
	v_pk_fma_f32 v[4:5], v[18:19], v[154:155], v[4:5]
	v_mov_b32_e32 v20, v7
	v_mov_b32_e32 v161, v162
	v_mov_b32_e32 v32, v45
	v_mov_b32_e32 v41, v81
	v_mul_f32_e32 v24, v33, v81
	v_pk_fma_f32 v[18:19], v[20:21], v[160:161], v[4:5]
	ds_read_b128 v[4:7], v87 offset:560
	v_pk_fma_f32 v[32:33], v[32:33], v[40:41], v[24:25] op_sel_hi:[1,1,0]
	v_mov_b32_e32 v24, v29
	v_mov_b32_e32 v33, v85
	v_mul_f32_e32 v28, v25, v85
	v_pk_fma_f32 v[24:25], v[24:25], v[32:33], v[28:29] op_sel_hi:[1,1,0]
	v_mov_b32_e32 v28, v200
	v_mov_b32_e32 v29, v50
	v_mul_f32_e32 v36, v50, v99
	s_waitcnt vmcnt(1)
	v_pk_fma_f32 v[44:45], v[28:29], v[116:117], v[36:37] op_sel_hi:[1,1,0]
	v_mov_b32_e32 v28, v38
	v_mov_b32_e32 v29, v42
	v_mov_b32_e32 v45, v77
	v_mul_f32_e32 v36, v42, v77
	v_mov_b32_e32 v20, v0
	s_waitcnt lgkmcnt(0)
	v_mov_b32_e32 v21, v4
	v_mov_b32_e32 v165, v166
	v_pk_fma_f32 v[116:117], v[28:29], v[44:45], v[36:37] op_sel_hi:[1,1,0]
	v_pk_fma_f32 v[18:19], v[20:21], v[164:165], v[18:19]
	v_mov_b32_e32 v4, v1
	v_mov_b32_e32 v49, v40
	v_pk_fma_f32 v[0:1], v[4:5], v[48:49], v[18:19]
	v_mov_b32_e32 v4, v2
	v_mov_b32_e32 v5, v6
	v_mov_b32_e32 v45, v116
	v_mov_b32_e32 v50, v201
	v_pk_fma_f32 v[4:5], v[4:5], v[44:45], v[0:1]
	v_mul_f32_e32 v0, v51, v99
	s_waitcnt vmcnt(0)
	v_pk_fma_f32 v[18:19], v[50:51], v[114:115], v[0:1] op_sel_hi:[1,1,0]
	v_mov_b32_e32 v42, v39
	v_mov_b32_e32 v19, v77
	v_mul_f32_e32 v0, v43, v77
	v_pk_fma_f32 v[0:1], v[42:43], v[18:19], v[0:1] op_sel_hi:[1,1,0]
	v_mov_b32_e32 v6, v3
	v_mov_b32_e32 v19, v0
	v_pk_fma_f32 v[60:61], v[6:7], v[18:19], v[4:5]
	v_pk_fma_f32 v[2:3], v[12:13], v[130:131], v[118:119]
	v_mov_b32_e32 v4, v10
	v_mov_b32_e32 v5, v14
	v_mov_b32_e32 v133, v8
	v_pk_fma_f32 v[2:3], v[4:5], v[132:133], v[2:3]
	v_mov_b32_e32 v14, v11
	ds_read_b128 v[4:7], v87 offset:1056
	ds_read_b128 v[10:13], v87 offset:1568
	v_mov_b32_e32 v139, v54
	v_pk_fma_f32 v[2:3], v[14:15], v[138:139], v[2:3]
	v_mov_b32_e32 v67, v52
	s_waitcnt lgkmcnt(1)
	v_mov_b32_e32 v14, v4
	s_waitcnt lgkmcnt(0)
	v_mov_b32_e32 v15, v10
	v_pk_fma_f32 v[2:3], v[14:15], v[66:67], v[2:3]
	v_mov_b32_e32 v10, v5
	v_mov_b32_e32 v137, v56
	v_pk_fma_f32 v[2:3], v[10:11], v[136:137], v[2:3]
	v_mov_b32_e32 v4, v6
	v_mov_b32_e32 v5, v12
	v_mov_b32_e32 v135, v58
	v_pk_fma_f32 v[2:3], v[4:5], v[134:135], v[2:3]
	v_mov_b32_e32 v12, v7
	v_mov_b32_e32 v125, v62
	v_pk_fma_f32 v[6:7], v[12:13], v[124:125], v[2:3]
	ds_read_b128 v[2:5], v87 offset:1072
	ds_read_b128 v[10:13], v87 offset:1584
	v_mov_b32_e32 v28, v46
	v_mov_b32_e32 v29, v34
	v_mov_b32_e32 v117, v81
	v_mul_f32_e32 v34, v34, v81
	v_pk_fma_f32 v[36:37], v[28:29], v[116:117], v[34:35] op_sel_hi:[1,1,0]
	v_mov_b32_e32 v28, v30
	v_mov_b32_e32 v29, v26
	v_mov_b32_e32 v37, v85
	v_mul_f32_e32 v26, v26, v85
	s_waitcnt lgkmcnt(1)
	v_mov_b32_e32 v14, v2
	s_waitcnt lgkmcnt(0)
	v_mov_b32_e32 v15, v10
	v_mov_b32_e32 v123, v64
	v_pk_fma_f32 v[28:29], v[28:29], v[36:37], v[26:27] op_sel_hi:[1,1,0]
	v_pk_fma_f32 v[6:7], v[14:15], v[122:123], v[6:7]
	v_mov_b32_e32 v10, v3
	v_mov_b32_e32 v33, v24
	v_mov_b32_e32 v34, v47
	v_mov_b32_e32 v1, v81
	v_pk_fma_f32 v[2:3], v[10:11], v[32:33], v[6:7]
	v_mov_b32_e32 v6, v4
	v_mov_b32_e32 v7, v12
	v_mov_b32_e32 v37, v28
	v_mul_f32_e32 v4, v35, v81
	v_pk_fma_f32 v[2:3], v[6:7], v[36:37], v[2:3]
	v_pk_fma_f32 v[6:7], v[34:35], v[0:1], v[4:5] op_sel_hi:[1,1,0]
	v_mov_b32_e32 v26, v31
	v_mov_b32_e32 v7, v85
	v_mul_f32_e32 v0, v27, v85
	v_pk_fma_f32 v[0:1], v[26:27], v[6:7], v[0:1] op_sel_hi:[1,1,0]
	v_mov_b32_e32 v12, v5
	v_mov_b32_e32 v7, v0
	v_pk_fma_f32 v[118:119], v[12:13], v[6:7], v[2:3]
	v_lshl_add_u64 v[2:3], v[100:101], 0, v[70:71]
	v_add_co_u32_e32 v4, vcc, s56, v2
	v_add_u32_e32 v87, 64, v87
	s_nop 0
	v_addc_co_u32_e32 v5, vcc, 0, v3, vcc
	v_add_co_u32_e32 v6, vcc, s57, v2
	v_lshl_add_u64 v[100:101], v[100:101], 0, s[12:13]
	s_nop 0
	v_addc_co_u32_e32 v7, vcc, 0, v3, vcc
	global_store_dword v[6:7], v104, off offset:-4096 nt
	global_store_dword v[4:5], v106, off offset:1024 nt
	global_store_dword v[4:5], v108, off offset:2048 nt
	global_store_dword v[4:5], v110, off offset:3072 nt
	global_store_dword v[6:7], v112, off nt
	global_store_dword v[6:7], v16, off offset:1024 nt
	global_store_dword v[6:7], v8, off offset:2048 nt
	global_store_dword v[6:7], v54, off offset:3072 nt
	v_add_co_u32_e32 v4, vcc, s60, v2
	s_nop 1
	v_addc_co_u32_e32 v5, vcc, 0, v3, vcc
	v_add_co_u32_e32 v2, vcc, s61, v2
	s_nop 1
	v_addc_co_u32_e32 v3, vcc, 0, v3, vcc
	global_store_dword v[2:3], v52, off offset:-4096 nt
	global_store_dword v[4:5], v56, off offset:1024 nt
	global_store_dword v[4:5], v58, off offset:2048 nt
	global_store_dword v[4:5], v62, off offset:3072 nt
	global_store_dword v[2:3], v64, off nt
	global_store_dword v[2:3], v24, off offset:1024 nt
	global_store_dword v[2:3], v28, off offset:2048 nt
	global_store_dword v[2:3], v0, off offset:3072 nt
	s_cbranch_scc1 .LBB0_317
	v_lshlrev_b32_e32 v68, 1, v68
	v_lshl_add_u64 v[0:1], v[72:73], 0, v[68:69]
	v_lshlrev_b64 v[2:3], 11, v[90:91]
	v_cvt_pk_bf16_f32 v4, v60, s0
	v_lshl_add_u64 v[2:3], v[0:1], 0, v[2:3]
	global_store_short v[2:3], v4, off
	v_lshlrev_b64 v[2:3], 11, v[92:93]
	v_cvt_pk_bf16_f32 v4, v61, s0
	v_lshl_add_u64 v[2:3], v[0:1], 0, v[2:3]
	global_store_short v[2:3], v4, off
	v_lshlrev_b64 v[2:3], 11, v[94:95]
	v_cvt_pk_bf16_f32 v4, v118, s0
	v_lshl_add_u64 v[2:3], v[0:1], 0, v[2:3]
	global_store_short v[2:3], v4, off
	v_lshlrev_b64 v[2:3], 11, v[96:97]
	s_add_i32 s16, s16, s8
	v_cvt_pk_bf16_f32 v4, v119, s0
	v_lshl_add_u64 v[0:1], v[0:1], 0, v[2:3]
	v_add_u32_e32 v76, s8, v76
	v_lshl_add_u64 v[78:79], v[78:79], 0, s[10:11]
	s_cmpk_lt_i32 s16, 0x200
	v_lshl_add_u64 v[82:83], v[82:83], 0, s[10:11]
	global_store_short v[0:1], v4, off
	s_cbranch_scc1 .LBB0_308

.LBB0_324:
	s_load_dwordx16 s[68:83], s[0:1], 0x40
	v_add_u32_e32 v1, s16, v168
	v_and_b32_e32 v2, 3, v1
	v_lshlrev_b32_e32 v0, 7, v2
	v_or_b32_e32 v3, v0, v180
	v_or_b32_e32 v4, v0, v181
	v_or_b32_e32 v5, v0, v182
	v_or_b32_e32 v6, v0, v183
	v_or_b32_e32 v7, v0, v185
	s_waitcnt vmcnt(22)
	v_or_b32_e32 v8, v0, v186
	v_or_b32_e32 v9, v0, v187
	v_or_b32_e32 v10, v0, v188
	v_lshlrev_b32_e32 v3, 2, v3
	v_lshlrev_b32_e32 v4, 2, v4
	v_lshlrev_b32_e32 v5, 2, v5
	v_lshlrev_b32_e32 v6, 2, v6
	v_lshlrev_b32_e32 v7, 2, v7
	v_lshlrev_b32_e32 v8, 2, v8
	v_lshlrev_b32_e32 v9, 2, v9
	v_lshlrev_b32_e32 v10, 2, v10
	s_waitcnt lgkmcnt(0)
	s_mov_b64 s[68:69], s[76:77]
	s_barrier
	global_load_dword v3, v3, s[68:69] nt
	s_nop 0
	global_load_dword v4, v4, s[68:69] nt
	s_nop 0
	global_load_dword v5, v5, s[68:69] nt
	s_nop 0
	global_load_dword v6, v6, s[68:69] nt
	s_nop 0
	global_load_dword v7, v7, s[68:69] nt
	s_nop 0
	global_load_dword v8, v8, s[68:69] nt
	s_nop 0
	global_load_dword v9, v9, s[68:69] nt
	s_nop 0
	global_load_dword v10, v10, s[68:69] nt
	s_mov_b64 s[70:71], s[78:79]
	s_mov_b64 s[72:73], s[80:81]
	s_waitcnt vmcnt(6)
	ds_write2st64_b32 v178, v3, v4 offset1:4
	s_waitcnt vmcnt(4)
	ds_write_b32 v184, v6
	s_waitcnt vmcnt(3)
	ds_write2st64_b32 v178, v5, v7 offset0:8 offset1:16
	s_waitcnt vmcnt(1)
	ds_write2st64_b32 v178, v8, v9 offset0:20 offset1:24
	s_waitcnt vmcnt(0)
	ds_write_b32 v189, v10
	s_and_saveexec_b64 s[14:15], s[4:5]
	s_cbranch_execz .LBB0_326
	s_load_dwordx16 s[68:83], s[0:1], 0x40
	v_or_b32_e32 v3, v0, v80
	v_lshlrev_b32_e32 v3, 2, v3
	s_waitcnt lgkmcnt(0)
	global_load_dword v3, v3, s[78:79] nt
	s_waitcnt vmcnt(0)
	ds_write_b32 v178, v3 offset:8192

.LBB0_333:
	v_lshl_add_u64 v[0:1], v[102:103], 0, v[70:71]
	global_load_dword v98, v[0:1], off nt
	global_load_dword v106, v[0:1], off offset:1024 nt
	global_load_dword v66, v[0:1], off offset:2048 nt
	global_load_dword v64, v[0:1], off offset:3072 nt
	v_add_co_u32_e32 v2, vcc, 0x1000, v0
	v_mov_b32_e32 v107, v99
	s_nop 0
	v_addc_co_u32_e32 v3, vcc, 0, v1, vcc
	global_load_dword v62, v[2:3], off nt
	global_load_dword v130, v[2:3], off offset:1024 nt
	global_load_dword v132, v[2:3], off offset:2048 nt
	global_load_dword v138, v[2:3], off offset:3072 nt
	v_add_co_u32_e32 v2, vcc, 0x2000, v0
	v_mov_b32_e32 v67, v99
	s_nop 0
	v_addc_co_u32_e32 v3, vcc, 0, v1, vcc
	global_load_dword v140, v[2:3], off nt
	global_load_dword v136, v[2:3], off offset:1024 nt
	global_load_dword v134, v[2:3], off offset:2048 nt
	global_load_dword v124, v[2:3], off offset:3072 nt
	v_add_co_u32_e32 v0, vcc, 0x3000, v0
	v_mov_b32_e32 v65, v99
	s_nop 0
	v_addc_co_u32_e32 v1, vcc, 0, v1, vcc
	global_load_dword v122, v[0:1], off nt
	global_load_dword v120, v[0:1], off offset:1024 nt
	global_load_dword v116, v[0:1], off offset:2048 nt
	global_load_dword v114, v[0:1], off offset:3072 nt
	ds_read_b128 v[0:3], v87 offset:4096
	ds_read_b128 v[52:55], v87 offset:2048
	ds_read_b128 v[56:59], v87 offset:4608
	ds_read_b128 v[12:15], v87 offset:2560
	ds_read_b128 v[8:11], v87 offset:5120
	ds_read_b128 v[48:51], v87 offset:3072
	ds_read_b128 v[44:47], v87 offset:5632
	ds_read_b128 v[40:43], v87 offset:3584
	ds_read_b128 v[36:39], v87 offset:4112
	ds_read_b128 v[24:27], v87 offset:2064
	s_waitcnt lgkmcnt(5)
	v_mov_b32_e32 v148, v8
	v_mov_b32_e32 v104, v0
	v_mov_b32_e32 v108, v1
	v_mov_b32_e32 v126, v2
	v_mov_b32_e32 v112, v3
	ds_read_b128 v[142:145], v87
	ds_read_b128 v[16:19], v87 offset:16
	ds_read_b128 v[4:7], v87 offset:32
	ds_read_b128 v[0:3], v87 offset:48
	ds_read_b128 v[28:31], v87 offset:4624
	ds_read_b128 v[32:35], v87 offset:2576
	ds_read_b128 v[20:23], v87 offset:528
	ds_read_b128 v[150:153], v87 offset:512
	v_mov_b32_e32 v105, v52
	s_waitcnt lgkmcnt(9)
	v_mov_b32_e32 v154, v36
	v_mul_f32_e32 v36, v52, v99
	v_mov_b32_e32 v109, v53
	v_mul_f32_e32 v8, v53, v99
	v_mov_b32_e32 v127, v54
	s_waitcnt lgkmcnt(7)
	v_mov_b32_e32 v146, v142
	s_waitcnt lgkmcnt(0)
	v_mov_b32_e32 v147, v150
	v_mov_b32_e32 v150, v143
	v_mov_b32_e32 v113, v55
	v_mov_b32_e32 v142, v10
	v_mul_f32_e32 v10, v55, v99
	v_mov_b32_e32 v155, v24
	v_mov_b32_e32 v63, v99
	v_mov_b32_e32 v149, v48
	v_mov_b32_e32 v143, v50
	v_mov_b32_e32 v131, v99
	v_mov_b32_e32 v133, v99
	v_mov_b32_e32 v139, v99
	v_mov_b32_e32 v141, v99
	v_mov_b32_e32 v137, v99
	v_mov_b32_e32 v135, v99
	v_mov_b32_e32 v125, v99
	v_mov_b32_e32 v123, v99
	v_mov_b32_e32 v121, v99
	v_mov_b32_e32 v117, v99
	v_mov_b32_e32 v115, v99
	s_add_i32 s14, s14, 16
	v_lshl_add_u64 v[102:103], v[102:103], 0, s[12:13]
	s_cmpk_lt_u32 s14, 0x70
	s_waitcnt vmcnt(15)
	v_pk_fma_f32 v[110:111], v[104:105], v[98:99], v[36:37] op_sel_hi:[1,1,0]
	v_mov_b32_e32 v104, v56
	v_mov_b32_e32 v105, v12
	v_mov_b32_e32 v111, v77
	v_mul_f32_e32 v12, v12, v77
	s_waitcnt vmcnt(14)
	v_pk_fma_f32 v[52:53], v[108:109], v[106:107], v[8:9] op_sel_hi:[1,1,0]
	v_pk_fma_f32 v[104:105], v[104:105], v[110:111], v[12:13] op_sel_hi:[1,1,0]
	v_mov_b32_e32 v12, v57
	v_mov_b32_e32 v53, v77
	v_mul_f32_e32 v8, v13, v77
	v_mov_b32_e32 v111, v104
	v_pk_fma_f32 v[106:107], v[12:13], v[52:53], v[8:9] op_sel_hi:[1,1,0]
	v_mul_f32_e32 v8, v54, v99
	v_pk_fma_f32 v[60:61], v[146:147], v[110:111], v[60:61]
	v_mov_b32_e32 v53, v106
	v_mov_b32_e32 v110, v9
	s_waitcnt vmcnt(13)
	v_pk_fma_f32 v[8:9], v[126:127], v[66:67], v[8:9] op_sel_hi:[1,1,0]
	v_pk_fma_f32 v[12:13], v[150:151], v[52:53], v[60:61]
	v_mov_b32_e32 v52, v58
	v_mov_b32_e32 v53, v14
	v_mov_b32_e32 v9, v77
	v_mul_f32_e32 v14, v14, v77
	v_pk_fma_f32 v[108:109], v[52:53], v[8:9], v[14:15] op_sel_hi:[1,1,0]
	v_mov_b32_e32 v52, v144
	v_mov_b32_e32 v53, v152
	v_mov_b32_e32 v9, v108
	v_pk_fma_f32 v[8:9], v[52:53], v[8:9], v[12:13]
	s_waitcnt vmcnt(12)
	v_pk_fma_f32 v[12:13], v[112:113], v[64:65], v[10:11] op_sel_hi:[1,1,0]
	v_mov_b32_e32 v14, v59
	v_mov_b32_e32 v13, v77
	v_mul_f32_e32 v10, v15, v77
	v_pk_fma_f32 v[112:113], v[14:15], v[12:13], v[10:11] op_sel_hi:[1,1,0]
	v_mul_f32_e32 v10, v24, v99
	v_mov_b32_e32 v152, v145
	v_mov_b32_e32 v13, v112
	v_mov_b32_e32 v146, v11
	s_waitcnt vmcnt(11)
	v_pk_fma_f32 v[10:11], v[154:155], v[62:63], v[10:11] op_sel_hi:[1,1,0]
	v_pk_fma_f32 v[8:9], v[152:153], v[12:13], v[8:9]
	v_mov_b32_e32 v12, v28
	v_mov_b32_e32 v13, v32
	v_mov_b32_e32 v11, v77
	v_mul_f32_e32 v14, v32, v77
	v_pk_fma_f32 v[144:145], v[12:13], v[10:11], v[14:15] op_sel_hi:[1,1,0]
	v_mov_b32_e32 v105, v81
	v_mov_b32_e32 v12, v16
	v_mov_b32_e32 v13, v20
	v_mov_b32_e32 v11, v144
	v_mul_f32_e32 v16, v48, v81
	v_pk_fma_f32 v[126:127], v[12:13], v[10:11], v[8:9]
	ds_read_b128 v[52:55], v87 offset:5136
	ds_read_b128 v[56:59], v87 offset:3088
	ds_read_b128 v[8:11], v87 offset:1040
	ds_read_b128 v[60:63], v87 offset:5648
	ds_read_b128 v[64:67], v87 offset:3600
	ds_read_b128 v[12:15], v87 offset:1552
	v_pk_fma_f32 v[158:159], v[148:149], v[104:105], v[16:17] op_sel_hi:[1,1,0]
	ds_read_b128 v[148:151], v87 offset:1024
	ds_read_b128 v[152:155], v87 offset:1536
	v_mov_b32_e32 v104, v44
	v_mov_b32_e32 v105, v40
	v_mov_b32_e32 v159, v85
	v_mul_f32_e32 v16, v40, v85
	v_mov_b32_e32 v111, v49
	v_mov_b32_e32 v107, v81
	v_pk_fma_f32 v[104:105], v[104:105], v[158:159], v[16:17] op_sel_hi:[1,1,0]
	v_mul_f32_e32 v16, v49, v81
	v_pk_fma_f32 v[48:49], v[110:111], v[106:107], v[16:17] op_sel_hi:[1,1,0]
	v_mov_b32_e32 v40, v45
	v_mov_b32_e32 v49, v85
	v_mul_f32_e32 v16, v41, v85
	v_mov_b32_e32 v109, v81
	s_waitcnt lgkmcnt(1)
	v_mov_b32_e32 v160, v148
	s_waitcnt lgkmcnt(0)
	v_mov_b32_e32 v161, v152
	v_mov_b32_e32 v159, v104
	v_pk_fma_f32 v[106:107], v[40:41], v[48:49], v[16:17] op_sel_hi:[1,1,0]
	v_mul_f32_e32 v16, v50, v81
	v_pk_fma_f32 v[118:119], v[160:161], v[158:159], v[118:119]
	v_mov_b32_e32 v152, v149
	v_mov_b32_e32 v49, v106
	v_pk_fma_f32 v[44:45], v[142:143], v[108:109], v[16:17] op_sel_hi:[1,1,0]
	v_pk_fma_f32 v[40:41], v[152:153], v[48:49], v[118:119]
	v_mov_b32_e32 v48, v46
	v_mov_b32_e32 v49, v42
	v_mov_b32_e32 v45, v85
	v_mul_f32_e32 v16, v42, v85
	v_pk_fma_f32 v[108:109], v[48:49], v[44:45], v[16:17] op_sel_hi:[1,1,0]
	v_mov_b32_e32 v147, v51
	v_mov_b32_e32 v113, v81
	v_mov_b32_e32 v48, v150
	v_mov_b32_e32 v49, v154
	v_mov_b32_e32 v45, v108
	v_mul_f32_e32 v16, v51, v81
	v_pk_fma_f32 v[40:41], v[48:49], v[44:45], v[40:41]
	v_pk_fma_f32 v[44:45], v[146:147], v[112:113], v[16:17] op_sel_hi:[1,1,0]
	v_mov_b32_e32 v42, v47
	v_mov_b32_e32 v45, v85
	v_mul_f32_e32 v16, v43, v85
	v_mov_b32_e32 v156, v52
	v_mov_b32_e32 v157, v56
	v_mov_b32_e32 v145, v81
	v_pk_fma_f32 v[110:111], v[42:43], v[44:45], v[16:17] op_sel_hi:[1,1,0]
	v_mul_f32_e32 v16, v56, v81
	v_mov_b32_e32 v154, v151
	v_mov_b32_e32 v45, v110
	v_pk_fma_f32 v[42:43], v[156:157], v[144:145], v[16:17] op_sel_hi:[1,1,0]
	v_pk_fma_f32 v[40:41], v[154:155], v[44:45], v[40:41]
	v_mov_b32_e32 v44, v60
	v_mov_b32_e32 v45, v64
	v_mov_b32_e32 v43, v85
	v_mul_f32_e32 v16, v64, v85
	v_pk_fma_f32 v[112:113], v[44:45], v[42:43], v[16:17] op_sel_hi:[1,1,0]
	v_mov_b32_e32 v44, v8
	v_mov_b32_e32 v24, v37
	v_mul_f32_e32 v8, v25, v99
	s_waitcnt vmcnt(10)
	v_pk_fma_f32 v[142:143], v[24:25], v[130:131], v[8:9] op_sel_hi:[1,1,0]
	v_mov_b32_e32 v32, v29
	v_mov_b32_e32 v143, v77
	v_mul_f32_e32 v8, v33, v77
	v_pk_fma_f32 v[24:25], v[32:33], v[142:143], v[8:9] op_sel_hi:[1,1,0]
	v_mov_b32_e32 v56, v53
	v_mov_b32_e32 v25, v81
	v_mul_f32_e32 v8, v57, v81
	v_pk_fma_f32 v[130:131], v[56:57], v[24:25], v[8:9] op_sel_hi:[1,1,0]
	v_mov_b32_e32 v64, v61
	v_mov_b32_e32 v131, v85
	v_mul_f32_e32 v8, v65, v85
	v_mov_b32_e32 v45, v12
	v_mov_b32_e32 v20, v17
	v_mov_b32_e32 v143, v24
	v_pk_fma_f32 v[16:17], v[64:65], v[130:131], v[8:9] op_sel_hi:[1,1,0]
	v_mov_b32_e32 v12, v9
	v_mov_b32_e32 v8, v38
	v_mov_b32_e32 v9, v26
	v_mul_f32_e32 v24, v26, v99
	s_waitcnt vmcnt(9)
	v_pk_fma_f32 v[144:145], v[8:9], v[132:133], v[24:25] op_sel_hi:[1,1,0]
	v_mov_b32_e32 v8, v30
	v_mov_b32_e32 v9, v34
	v_mov_b32_e32 v145, v77
	v_mul_f32_e32 v24, v34, v77
	v_pk_fma_f32 v[146:147], v[8:9], v[144:145], v[24:25] op_sel_hi:[1,1,0]
	v_mov_b32_e32 v8, v54
	v_mov_b32_e32 v9, v58
	v_mov_b32_e32 v147, v81
	v_mul_f32_e32 v24, v58, v81
	v_pk_fma_f32 v[132:133], v[8:9], v[146:147], v[24:25] op_sel_hi:[1,1,0]
	v_mov_b32_e32 v8, v62
	v_mov_b32_e32 v9, v66
	v_mov_b32_e32 v133, v85
	v_mul_f32_e32 v24, v66, v85
	v_pk_fma_f32 v[8:9], v[8:9], v[132:133], v[24:25] op_sel_hi:[1,1,0]
	v_mov_b32_e32 v26, v39
	v_mul_f32_e32 v24, v27, v99
	s_waitcnt vmcnt(8)
	v_pk_fma_f32 v[152:153], v[26:27], v[138:139], v[24:25] op_sel_hi:[1,1,0]
	v_mov_b32_e32 v34, v31
	v_mov_b32_e32 v153, v77
	v_mul_f32_e32 v24, v35, v77
	v_pk_fma_f32 v[156:157], v[34:35], v[152:153], v[24:25] op_sel_hi:[1,1,0]
	v_mov_b32_e32 v58, v55
	v_mov_b32_e32 v157, v81
	v_mul_f32_e32 v24, v59, v81
	v_pk_fma_f32 v[138:139], v[58:59], v[156:157], v[24:25] op_sel_hi:[1,1,0]
	v_mov_b32_e32 v66, v63
	v_mov_b32_e32 v139, v85
	v_mul_f32_e32 v24, v67, v85
	v_pk_fma_f32 v[54:55], v[66:67], v[138:139], v[24:25] op_sel_hi:[1,1,0]
	ds_read_b128 v[62:65], v87 offset:4128
	ds_read_b128 v[24:27], v87 offset:2080
	v_mov_b32_e32 v43, v112
	v_pk_fma_f32 v[118:119], v[44:45], v[42:43], v[40:41]
	v_pk_fma_f32 v[20:21], v[20:21], v[142:143], v[126:127]
	s_waitcnt lgkmcnt(1)
	v_mov_b32_e32 v28, v62
	s_waitcnt lgkmcnt(0)
	v_mov_b32_e32 v29, v24
	v_mul_f32_e32 v24, v24, v99
	s_waitcnt vmcnt(7)
	v_pk_fma_f32 v[60:61], v[28:29], v[140:141], v[24:25] op_sel_hi:[1,1,0]
	ds_read_b128 v[32:35], v87 offset:4640
	ds_read_b128 v[28:31], v87 offset:2592
	v_mov_b32_e32 v61, v77
	v_mov_b32_e32 v145, v146
	v_mov_b32_e32 v153, v156
	s_waitcnt lgkmcnt(1)
	v_mov_b32_e32 v36, v32
	s_waitcnt lgkmcnt(0)
	v_mov_b32_e32 v37, v28
	v_mul_f32_e32 v24, v28, v77
	v_pk_fma_f32 v[140:141], v[36:37], v[60:61], v[24:25] op_sel_hi:[1,1,0]
	ds_read_b128 v[40:43], v87 offset:5152
	ds_read_b128 v[36:39], v87 offset:3104
	v_mov_b32_e32 v141, v81
	v_mul_f32_e32 v28, v25, v99
	v_mov_b32_e32 v61, v140
	s_waitcnt lgkmcnt(1)
	v_mov_b32_e32 v44, v40
	s_waitcnt lgkmcnt(0)
	v_mov_b32_e32 v45, v36
	v_mul_f32_e32 v24, v36, v81
	v_pk_fma_f32 v[66:67], v[44:45], v[140:141], v[24:25] op_sel_hi:[1,1,0]
	ds_read_b128 v[48:51], v87 offset:5664
	ds_read_b128 v[44:47], v87 offset:3616
	v_mov_b32_e32 v67, v85
	v_mov_b32_e32 v36, v41
	v_mov_b32_e32 v131, v16
	s_waitcnt lgkmcnt(1)
	v_mov_b32_e32 v52, v48
	s_waitcnt lgkmcnt(0)
	v_mov_b32_e32 v53, v44
	v_mul_f32_e32 v24, v44, v85
	v_pk_fma_f32 v[52:53], v[52:53], v[66:67], v[24:25] op_sel_hi:[1,1,0]
	v_mov_b32_e32 v24, v63
	s_waitcnt vmcnt(6)
	v_pk_fma_f32 v[148:149], v[24:25], v[136:137], v[28:29] op_sel_hi:[1,1,0]
	v_mov_b32_e32 v28, v33
	v_mov_b32_e32 v149, v77
	v_mul_f32_e32 v24, v29, v77
	v_pk_fma_f32 v[150:151], v[28:29], v[148:149], v[24:25] op_sel_hi:[1,1,0]
	v_mul_f32_e32 v24, v37, v81
	v_mov_b32_e32 v151, v81
	v_pk_fma_f32 v[136:137], v[36:37], v[150:151], v[24:25] op_sel_hi:[1,1,0]
	v_mov_b32_e32 v44, v49
	v_mov_b32_e32 v137, v85
	v_mul_f32_e32 v24, v45, v85
	v_pk_fma_f32 v[56:57], v[44:45], v[136:137], v[24:25] op_sel_hi:[1,1,0]
	v_mov_b32_e32 v24, v64
	v_mov_b32_e32 v25, v26
	v_mul_f32_e32 v26, v26, v99
	s_waitcnt vmcnt(5)
	v_pk_fma_f32 v[154:155], v[24:25], v[134:135], v[26:27] op_sel_hi:[1,1,0]
	v_mov_b32_e32 v24, v34
	v_mov_b32_e32 v25, v30
	v_mov_b32_e32 v155, v77
	v_mul_f32_e32 v26, v30, v77
	v_pk_fma_f32 v[158:159], v[24:25], v[154:155], v[26:27] op_sel_hi:[1,1,0]
	v_mov_b32_e32 v24, v42
	v_mov_b32_e32 v25, v38
	v_mov_b32_e32 v159, v81
	v_mul_f32_e32 v26, v38, v81
	v_pk_fma_f32 v[134:135], v[24:25], v[158:159], v[26:27] op_sel_hi:[1,1,0]
	v_mov_b32_e32 v24, v50
	v_mov_b32_e32 v25, v46
	v_mov_b32_e32 v135, v85
	v_mul_f32_e32 v26, v46, v85
	v_pk_fma_f32 v[58:59], v[24:25], v[134:135], v[26:27] op_sel_hi:[1,1,0]
	v_mov_b32_e32 v26, v65
	v_mul_f32_e32 v24, v27, v99
	s_waitcnt vmcnt(4)
	v_pk_fma_f32 v[160:161], v[26:27], v[124:125], v[24:25] op_sel_hi:[1,1,0]
	v_mov_b32_e32 v30, v35
	v_mov_b32_e32 v161, v77
	v_mul_f32_e32 v24, v31, v77
	v_pk_fma_f32 v[162:163], v[30:31], v[160:161], v[24:25] op_sel_hi:[1,1,0]
	v_mov_b32_e32 v46, v51
	ds_read_b128 v[198:201], v87 offset:4144
	ds_read_b128 v[48:51], v87 offset:2096
	v_mov_b32_e32 v38, v43
	v_mov_b32_e32 v163, v81
	v_mul_f32_e32 v24, v39, v81
	v_pk_fma_f32 v[124:125], v[38:39], v[162:163], v[24:25] op_sel_hi:[1,1,0]
	ds_read_b128 v[36:39], v87 offset:4656
	ds_read_b128 v[40:43], v87 offset:2608
	v_mov_b32_e32 v125, v85
	v_mul_f32_e32 v24, v47, v85
	v_pk_fma_f32 v[62:63], v[46:47], v[124:125], v[24:25] op_sel_hi:[1,1,0]
	ds_read_b128 v[44:47], v87 offset:5168
	ds_read_b128 v[32:35], v87 offset:3120
	s_waitcnt lgkmcnt(5)
	v_mov_b32_e32 v24, v198
	s_waitcnt lgkmcnt(4)
	v_mov_b32_e32 v25, v48
	v_mul_f32_e32 v26, v48, v99
	s_waitcnt vmcnt(3)
	v_pk_fma_f32 v[164:165], v[24:25], v[122:123], v[26:27] op_sel_hi:[1,1,0]
	s_waitcnt lgkmcnt(3)
	v_mov_b32_e32 v24, v36
	s_waitcnt lgkmcnt(2)
	v_mov_b32_e32 v25, v40
	v_mov_b32_e32 v165, v77
	v_mul_f32_e32 v26, v40, v77
	v_pk_fma_f32 v[166:167], v[24:25], v[164:165], v[26:27] op_sel_hi:[1,1,0]
	s_waitcnt lgkmcnt(1)
	v_mov_b32_e32 v24, v44
	s_waitcnt lgkmcnt(0)
	v_mov_b32_e32 v25, v32
	v_mov_b32_e32 v167, v81
	v_mul_f32_e32 v26, v32, v81
	v_pk_fma_f32 v[122:123], v[24:25], v[166:167], v[26:27] op_sel_hi:[1,1,0]
	ds_read_b128 v[28:31], v87 offset:5680
	ds_read_b128 v[24:27], v87 offset:3632
	v_mov_b32_e32 v123, v85
	v_mov_b32_e32 v48, v199
	v_mov_b32_e32 v149, v150
	s_waitcnt lgkmcnt(1)
	v_mov_b32_e32 v64, v28
	s_waitcnt lgkmcnt(0)
	v_mov_b32_e32 v65, v24
	v_mul_f32_e32 v24, v24, v85
	v_pk_fma_f32 v[64:65], v[64:65], v[122:123], v[24:25] op_sel_hi:[1,1,0]
	v_mul_f32_e32 v24, v49, v99
	s_waitcnt vmcnt(2)
	v_pk_fma_f32 v[48:49], v[48:49], v[120:121], v[24:25] op_sel_hi:[1,1,0]
	v_mov_b32_e32 v120, v18
	v_mov_b32_e32 v121, v22
	v_pk_fma_f32 v[20:21], v[120:121], v[144:145], v[20:21]
	v_mov_b32_e32 v22, v19
	v_pk_fma_f32 v[22:23], v[22:23], v[152:153], v[20:21]
	ds_read_b128 v[18:21], v87 offset:544
	v_mov_b32_e32 v120, v4
	v_mov_b32_e32 v40, v37
	v_mov_b32_e32 v49, v77
	v_mul_f32_e32 v24, v41, v77
	s_waitcnt lgkmcnt(0)
	v_mov_b32_e32 v121, v18
	v_pk_fma_f32 v[22:23], v[120:121], v[60:61], v[22:23]
	v_mov_b32_e32 v18, v5
	v_pk_fma_f32 v[4:5], v[18:19], v[148:149], v[22:23]
	v_mov_b32_e32 v18, v6
	v_mov_b32_e32 v19, v20
	v_mov_b32_e32 v155, v158
	v_pk_fma_f32 v[40:41], v[40:41], v[48:49], v[24:25] op_sel_hi:[1,1,0]
	v_pk_fma_f32 v[4:5], v[18:19], v[154:155], v[4:5]
	v_mov_b32_e32 v20, v7
	v_mov_b32_e32 v161, v162
	v_mov_b32_e32 v32, v45
	v_mov_b32_e32 v41, v81
	v_mul_f32_e32 v24, v33, v81
	v_pk_fma_f32 v[18:19], v[20:21], v[160:161], v[4:5]
	ds_read_b128 v[4:7], v87 offset:560
	v_pk_fma_f32 v[32:33], v[32:33], v[40:41], v[24:25] op_sel_hi:[1,1,0]
	v_mov_b32_e32 v24, v29
	v_mov_b32_e32 v33, v85
	v_mul_f32_e32 v28, v25, v85
	v_pk_fma_f32 v[24:25], v[24:25], v[32:33], v[28:29] op_sel_hi:[1,1,0]
	v_mov_b32_e32 v28, v200
	v_mov_b32_e32 v29, v50
	v_mul_f32_e32 v36, v50, v99
	s_waitcnt vmcnt(1)
	v_pk_fma_f32 v[44:45], v[28:29], v[116:117], v[36:37] op_sel_hi:[1,1,0]
	v_mov_b32_e32 v28, v38
	v_mov_b32_e32 v29, v42
	v_mov_b32_e32 v45, v77
	v_mul_f32_e32 v36, v42, v77
	v_mov_b32_e32 v20, v0
	s_waitcnt lgkmcnt(0)
	v_mov_b32_e32 v21, v4
	v_mov_b32_e32 v165, v166
	v_pk_fma_f32 v[116:117], v[28:29], v[44:45], v[36:37] op_sel_hi:[1,1,0]
	v_pk_fma_f32 v[18:19], v[20:21], v[164:165], v[18:19]
	v_mov_b32_e32 v4, v1
	v_mov_b32_e32 v49, v40
	v_pk_fma_f32 v[0:1], v[4:5], v[48:49], v[18:19]
	v_mov_b32_e32 v4, v2
	v_mov_b32_e32 v5, v6
	v_mov_b32_e32 v45, v116
	v_mov_b32_e32 v50, v201
	v_pk_fma_f32 v[4:5], v[4:5], v[44:45], v[0:1]
	v_mul_f32_e32 v0, v51, v99
	s_waitcnt vmcnt(0)
	v_pk_fma_f32 v[18:19], v[50:51], v[114:115], v[0:1] op_sel_hi:[1,1,0]
	v_mov_b32_e32 v42, v39
	v_mov_b32_e32 v19, v77
	v_mul_f32_e32 v0, v43, v77
	v_pk_fma_f32 v[0:1], v[42:43], v[18:19], v[0:1] op_sel_hi:[1,1,0]
	v_mov_b32_e32 v6, v3
	v_mov_b32_e32 v19, v0
	v_pk_fma_f32 v[60:61], v[6:7], v[18:19], v[4:5]
	v_pk_fma_f32 v[2:3], v[12:13], v[130:131], v[118:119]
	v_mov_b32_e32 v4, v10
	v_mov_b32_e32 v5, v14
	v_mov_b32_e32 v133, v8
	v_pk_fma_f32 v[2:3], v[4:5], v[132:133], v[2:3]
	v_mov_b32_e32 v14, v11
	ds_read_b128 v[4:7], v87 offset:1056
	ds_read_b128 v[10:13], v87 offset:1568
	v_mov_b32_e32 v139, v54
	v_pk_fma_f32 v[2:3], v[14:15], v[138:139], v[2:3]
	v_mov_b32_e32 v67, v52
	s_waitcnt lgkmcnt(1)
	v_mov_b32_e32 v14, v4
	s_waitcnt lgkmcnt(0)
	v_mov_b32_e32 v15, v10
	v_pk_fma_f32 v[2:3], v[14:15], v[66:67], v[2:3]
	v_mov_b32_e32 v10, v5
	v_mov_b32_e32 v137, v56
	v_pk_fma_f32 v[2:3], v[10:11], v[136:137], v[2:3]
	v_mov_b32_e32 v4, v6
	v_mov_b32_e32 v5, v12
	v_mov_b32_e32 v135, v58
	v_pk_fma_f32 v[2:3], v[4:5], v[134:135], v[2:3]
	v_mov_b32_e32 v12, v7
	v_mov_b32_e32 v125, v62
	v_pk_fma_f32 v[6:7], v[12:13], v[124:125], v[2:3]
	ds_read_b128 v[2:5], v87 offset:1072
	ds_read_b128 v[10:13], v87 offset:1584
	v_mov_b32_e32 v28, v46
	v_mov_b32_e32 v29, v34
	v_mov_b32_e32 v117, v81
	v_mul_f32_e32 v34, v34, v81
	v_pk_fma_f32 v[36:37], v[28:29], v[116:117], v[34:35] op_sel_hi:[1,1,0]
	v_mov_b32_e32 v28, v30
	v_mov_b32_e32 v29, v26
	v_mov_b32_e32 v37, v85
	v_mul_f32_e32 v26, v26, v85
	s_waitcnt lgkmcnt(1)
	v_mov_b32_e32 v14, v2
	s_waitcnt lgkmcnt(0)
	v_mov_b32_e32 v15, v10
	v_mov_b32_e32 v123, v64
	v_pk_fma_f32 v[28:29], v[28:29], v[36:37], v[26:27] op_sel_hi:[1,1,0]
	v_pk_fma_f32 v[6:7], v[14:15], v[122:123], v[6:7]
	v_mov_b32_e32 v10, v3
	v_mov_b32_e32 v33, v24
	v_mov_b32_e32 v34, v47
	v_mov_b32_e32 v1, v81
	v_pk_fma_f32 v[2:3], v[10:11], v[32:33], v[6:7]
	v_mov_b32_e32 v6, v4
	v_mov_b32_e32 v7, v12
	v_mov_b32_e32 v37, v28
	v_mul_f32_e32 v4, v35, v81
	v_pk_fma_f32 v[2:3], v[6:7], v[36:37], v[2:3]
	v_pk_fma_f32 v[6:7], v[34:35], v[0:1], v[4:5] op_sel_hi:[1,1,0]
	v_mov_b32_e32 v26, v31
	v_mov_b32_e32 v7, v85
	v_mul_f32_e32 v0, v27, v85
	v_pk_fma_f32 v[0:1], v[26:27], v[6:7], v[0:1] op_sel_hi:[1,1,0]
	v_mov_b32_e32 v12, v5
	v_mov_b32_e32 v7, v0
	v_pk_fma_f32 v[118:119], v[12:13], v[6:7], v[2:3]
	v_lshl_add_u64 v[2:3], v[100:101], 0, v[70:71]
	v_add_co_u32_e32 v4, vcc, s54, v2
	v_add_u32_e32 v87, 64, v87
	s_nop 0
	v_addc_co_u32_e32 v5, vcc, 0, v3, vcc
	v_add_co_u32_e32 v6, vcc, s55, v2
	v_lshl_add_u64 v[100:101], v[100:101], 0, s[12:13]
	s_nop 0
	v_addc_co_u32_e32 v7, vcc, 0, v3, vcc
	global_store_dword v[6:7], v104, off offset:-4096 nt
	global_store_dword v[4:5], v106, off offset:1024 nt
	global_store_dword v[4:5], v108, off offset:2048 nt
	global_store_dword v[4:5], v110, off offset:3072 nt
	global_store_dword v[6:7], v112, off nt
	global_store_dword v[6:7], v16, off offset:1024 nt
	global_store_dword v[6:7], v8, off offset:2048 nt
	global_store_dword v[6:7], v54, off offset:3072 nt
	v_add_co_u32_e32 v4, vcc, s56, v2
	s_nop 1
	v_addc_co_u32_e32 v5, vcc, 0, v3, vcc
	v_add_co_u32_e32 v2, vcc, s57, v2
	s_nop 1
	v_addc_co_u32_e32 v3, vcc, 0, v3, vcc
	global_store_dword v[2:3], v52, off offset:-4096 nt
	global_store_dword v[4:5], v56, off offset:1024 nt
	global_store_dword v[4:5], v58, off offset:2048 nt
	global_store_dword v[4:5], v62, off offset:3072 nt
	global_store_dword v[2:3], v64, off nt
	global_store_dword v[2:3], v24, off offset:1024 nt
	global_store_dword v[2:3], v28, off offset:2048 nt
	global_store_dword v[2:3], v0, off offset:3072 nt
	s_cbranch_scc1 .LBB0_333
	v_lshlrev_b32_e32 v68, 1, v68
	v_lshl_add_u64 v[0:1], v[72:73], 0, v[68:69]
	v_lshlrev_b64 v[2:3], 11, v[90:91]
	v_cvt_pk_bf16_f32 v4, v60, s0
	v_lshl_add_u64 v[2:3], v[0:1], 0, v[2:3]
	global_store_short v[2:3], v4, off
	v_lshlrev_b64 v[2:3], 11, v[92:93]
	v_cvt_pk_bf16_f32 v4, v61, s0
	v_lshl_add_u64 v[2:3], v[0:1], 0, v[2:3]
	global_store_short v[2:3], v4, off
	v_lshlrev_b64 v[2:3], 11, v[94:95]
	v_cvt_pk_bf16_f32 v4, v118, s0
	v_lshl_add_u64 v[2:3], v[0:1], 0, v[2:3]
	global_store_short v[2:3], v4, off
	v_lshlrev_b64 v[2:3], 11, v[96:97]
	s_add_i32 s16, s8, s16
	v_cvt_pk_bf16_f32 v4, v119, s0
	v_lshl_add_u64 v[0:1], v[0:1], 0, v[2:3]
	v_add_u32_e32 v76, s8, v76
	v_lshl_add_u64 v[78:79], v[78:79], 0, s[10:11]
	s_cmpk_gt_i32 s16, 0x1ff
	v_lshl_add_u64 v[82:83], v[82:83], 0, s[10:11]
	global_store_short v[0:1], v4, off
	s_cbranch_scc0 .LBB0_324
